# GEMM1a alternative tile order with the column-tile index rotated by the round, so every WG sees all epilogue types (balanced epilogue cost per WG); on top of ordb
# speedup vs baseline: 1.0075x; 1.0028x over previous
;     __device__ bool next(int i, Unit& u) const {
;         const int ti = halves == 2 ? (i >> 1) : i; u.half = halves == 2 ? (i & 1) : 0;
;     ...
;         if (G == 256 && nM == 32 && (nN & 7) == 0) {
;             if (ti >= (nN >> 3)) return false;
;             const int x = c & 7, j = c >> 3; u.pm = 4 * x + (j & 3); u.pn = 8 * ti + (j >> 2); return true;
;         }
;     ...
;         const long L = (long)ti * G + c; if (L >= nwg) return false;
;         int wgid = (int)L; { const int q = nwg / NXCD, r = nwg % NXCD, xcd = wgid % NXCD, off = wgid / NXCD; wgid = (xcd < r ? xcd * (q + 1) : r * (q + 1) + (xcd - r) * q) + off; }
;         const int nig = wgm * nN, gid = wgid / nig, fm = gid * wgm, gsz = (nM - fm) < wgm ? (nM - fm) : wgm;
;         u.pm = fm + ((wgid % nig) % gsz); u.pn = (wgid % nig) / gsz; return true;
.LBB0_99:
	s_ashr_i32 s5, s5, 3
	s_add_i32 s5, s29, s5
	s_ashr_i32 s26, s5, 31
	s_lshr_b32 s26, s26, 23
	s_add_i32 s26, s5, s26
	s_ashr_i32 s27, s26, 9
	s_lshl_b32 s27, s27, 3
	s_sub_i32 s28, 32, s27
	s_min_i32 s28, s28, 8
	s_abs_i32 s29, s28
	v_cvt_f32_u32_e32 v0, s29
	s_sub_i32 s43, 0, s29
	s_and_b32 s26, s26, 0xfffffe00
	s_sub_i32 s5, s5, s26
	v_rcp_iflag_f32_e32 v0, v0
	s_abs_i32 s26, s5
	s_xor_b32 s42, s5, s28
	s_ashr_i32 s42, s42, 31
	v_mul_f32_e32 v0, 0x4f7ffffe, v0
	v_cvt_u32_f32_e32 v0, v0
	s_nop 0
	v_readfirstlane_b32 s44, v0
	s_mul_i32 s43, s43, s44
	s_mul_hi_u32 s43, s44, s43
	s_add_i32 s44, s44, s43
	s_mul_hi_u32 s43, s26, s44
	s_mul_i32 s44, s43, s29
	s_sub_i32 s26, s26, s44
	s_add_i32 s45, s43, 1
	s_sub_i32 s44, s26, s29
	s_cmp_ge_u32 s26, s29
	s_cselect_b32 s43, s45, s43
	s_cselect_b32 s26, s44, s26
	s_add_i32 s44, s43, 1
	s_cmp_ge_u32 s26, s29
	s_cselect_b32 s26, s44, s43
	s_xor_b32 s26, s26, s42
	s_sub_i32 s26, s26, s42
	s_mul_i32 s28, s26, s28
	s_sub_i32 s5, s5, s28
	s_add_i32 s28, s27, s5
	s_and_b32 s28, s2, 7
	s_lshl_b32 s28, s28, 2
	s_bfe_u32 s5, s2, 0x20003
	s_or_b32 s28, s28, s5
	s_lshl_b32 s26, s62, 3
	s_lshr_b32 s5, s2, 5
	s_add_i32 s5, s5, s62
	s_and_b32 s5, s5, 7
	s_add_i32 s26, s26, s5
